# hgrn pass2 decay-factor section hand-written (packed f32, scalar branch on wave-uniform quarter); plus all previous
# speedup vs baseline: 1.0579x; 1.0017x over previous
.LBB0_268:
	s_lshl_b32 s18, s18, 10
	s_and_b32 s10, s10, 1
	s_ashr_i32 s0, s3, 7
	s_xor_b32 s19, s18, 0x1f80
	s_ashr_i32 s1, s0, 31
	s_lshl_b32 s4, s10, 25
	v_readlane_b32 s5, v250, 42
	s_add_u32 s20, s5, s4
	v_readlane_b32 s4, v250, 43
	s_addc_u32 s24, s4, 0
	s_lshl_b64 s[4:5], s[0:1], 24
	s_add_u32 s20, s20, s4
	s_addc_u32 s33, s24, s5
	v_readlane_b32 s0, v250, 44
	s_add_u32 s0, s0, s4
	v_readlane_b32 s1, v250, 45
	s_addc_u32 s1, s1, s5
	s_lshl_b32 s24, s3, 4
	s_and_b32 s36, s24, 0x700
	s_add_u32 s29, s0, s36
	s_addc_u32 s24, s1, 0
	s_cmp_eq_u32 s10, 0
	s_cselect_b64 s[48:49], -1, 0
	s_and_b64 s[0:1], s[48:49], exec
	s_cselect_b32 s1, s8, s76
	s_cselect_b32 s0, s9, s28
	s_add_u32 s37, s1, s4
	s_addc_u32 s50, s0, s5
	s_lshl_b32 s0, s54, 4
	s_ashr_i32 s1, s0, 31
	s_add_u32 s51, s80, s4
	s_addc_u32 s52, s81, s5
	s_add_u32 s25, s20, s36
	s_addc_u32 s10, s33, 0
	s_and_b64 s[4:5], s[48:49], exec
	s_cselect_b32 s56, 0x800, s78
	s_add_u32 s20, s37, s36
	s_addc_u32 s33, s50, 0
	s_lshl_b64 s[4:5], s[0:1], 1
	s_add_u32 s4, s20, s4
	s_addc_u32 s5, s33, s5
	s_add_u32 s33, s51, s36
	s_addc_u32 s20, s52, 0
	s_lshl_b32 s1, s21, 10
	v_cndmask_b32_e64 v32, v105, v99, s[48:49]
	s_xor_b32 s21, s1, 0x1fc0
	s_waitcnt vmcnt(0)
	v_lshl_or_b32 v66, v32, 11, v152
	s_and_b64 s[36:37], s[48:49], exec
	s_cselect_b32 s1, s1, s21
	v_add_u32_e32 v68, s56, v66
	s_lshl_b32 s1, s1, 11
	s_waitcnt vmcnt(38)
	v_add_u32_e32 v70, s56, v68
	s_add_u32 s36, s33, s1
	v_add_u32_e32 v72, s56, v70
	s_addc_u32 s37, s20, 0
	s_waitcnt vmcnt(29)
	v_add_u32_e32 v74, s56, v72
	s_add_u32 s50, s25, s1
	v_add_u32_e32 v76, s56, v74
	s_addc_u32 s51, s10, 0
	s_waitcnt vmcnt(28)
	v_add_u32_e32 v78, s56, v76
	s_add_u32 s52, s29, s1
	v_add_u32_e32 v80, s56, v78
	s_addc_u32 s53, s24, 0
	s_waitcnt vmcnt(19)
	v_add_u32_e32 v82, s56, v80
	v_add_u32_e32 v84, s56, v82
	s_waitcnt vmcnt(26)
	v_add_u32_e32 v86, s56, v84
	v_add_u32_e32 v88, s56, v86
	s_waitcnt vmcnt(20)
	v_add_u32_e32 v90, s56, v88
	v_add_u32_e32 v92, s56, v90
	s_waitcnt vmcnt(22)
	v_add_u32_e32 v94, s56, v92
	v_add_u32_e32 v96, s56, v94
	v_mbcnt_lo_u32_b32 v246, -1, 0
	v_mbcnt_hi_u32_b32 v246, -1, v246
	v_and_b32_e32 v247, 7, v246
	v_lshrrev_b32_e32 v248, 3, v246
	v_lshlrev_b32_e32 v247, 4, v247
	v_lshlrev_b32_e32 v249, 1, v246
	v_sub_u32_e32 v247, v247, v249
	v_mul_lo_u32 v248, v248, s56
	v_add3_u32 v244, v66, v247, v248
	v_lshl_add_u32 v245, s56, 3, v244
	v_lshl_add_u32 v246, v246, 1, s100
	s_add_i32 m0, s100, 0
	s_nop 0
	global_load_lds_dwordx4 v244, s[50:51]
	s_add_i32 m0, s100, 1024
	s_nop 0
	global_load_lds_dwordx4 v245, s[50:51]
	s_add_i32 m0, s100, 2048
	s_nop 0
	global_load_lds_dwordx4 v244, s[52:53]
	s_add_i32 m0, s100, 3072
	s_nop 0
	global_load_lds_dwordx4 v245, s[52:53]
	s_add_i32 m0, s100, 4096
	s_nop 0
	global_load_lds_dwordx4 v244, s[36:37]
	s_add_i32 m0, s100, 5120
	s_nop 0
	global_load_lds_dwordx4 v245, s[36:37]
	s_ashr_i32 s50, s55, 7
	s_lshl_b32 s1, s54, 1
	s_and_b32 s51, s1, 2
	s_lshl_b32 s1, s50, 4
	v_lshlrev_b32_e32 v32, 1, v98
	v_mov_b32_e32 v33, v64
	s_cmp_gt_u32 s50, 1
	v_lshl_add_u64 v[112:113], s[4:5], 0, v[32:33]
	v_add_u32_e32 v238, s18, v98
	v_sub_u32_e32 v239, s19, v98
	v_add_u32_e32 v239, 0x7f, v239
	v_cndmask_b32_e64 v238, v239, v238, s[48:49]
	v_lshlrev_b32_e32 v238, 11, v238
	v_lshl_add_u32 v238, v109, 1, v238
	v_mov_b32_e32 v239, 0
	v_lshl_add_u64 v[228:229], s[4:5], 0, v[238:239]
	v_mov_b32_e32 v238, 0x8000
	v_mov_b32_e32 v240, 0xffff8000
	v_cndmask_b32_e64 v238, v240, v238, s[48:49]
	v_cndmask_b32_e64 v239, -1, 0, s[48:49]
	v_lshl_add_u64 v[230:231], v[228:229], 0, v[238:239]
	v_lshl_add_u64 v[232:233], v[230:231], 0, v[238:239]
	v_lshl_add_u64 v[234:235], v[232:233], 0, v[238:239]
	v_lshlrev_b32_e32 v236, 2, v238
	v_mov_b32_e32 v237, v239
	v_mov_b32_e32 v248, 0x3fb8aa3b
	v_mov_b32_e32 v249, 0x3fb8aa3b
	v_mov_b32_e32 v238, 1.0
	v_mov_b32_e32 v239, 1.0
	v_mov_b32_e32 v247, 0x42e6d4ca
	s_cselect_b64 s[4:5], -1, 0
	s_cmp_le_i32 s51, s50
	s_movk_i32 s53, 0x110
	s_movk_i32 s52, 0x90
	v_or_b32_e32 v114, s18, v109
	s_mov_b32 s21, 0
	v_mov_b32_e32 v67, v64
	v_mov_b32_e32 v69, v64
	v_mov_b32_e32 v71, v64
	v_mov_b32_e32 v73, v64
	v_mov_b32_e32 v75, v64
	v_mov_b32_e32 v77, v64
	v_mov_b32_e32 v79, v64
	v_mov_b32_e32 v81, v64
	v_mov_b32_e32 v83, v64
	v_mov_b32_e32 v85, v64
	v_mov_b32_e32 v87, v64
	v_mov_b32_e32 v89, v64
	v_mov_b32_e32 v91, v64
	v_mov_b32_e32 v93, v64
	v_mov_b32_e32 v95, v64
	v_mov_b32_e32 v97, v64
	v_or_b32_e32 v40, s1, v109
	v_or_b32_e32 v41, s1, v98
	v_or_b32_e32 v42, s0, v98
	s_cselect_b64 s[0:1], -1, 0
	s_cmp_eq_u32 s51, 0
	s_cselect_b64 s[36:37], -1, 0
	s_and_b64 s[4:5], s[4:5], s[36:37]
	s_and_b64 s[4:5], s[4:5], exec
	s_mov_b32 s4, 0xcc00
	s_cselect_b32 s4, s4, 0x4400
	s_add_i32 s4, s4, 0
	s_lshl_b32 s5, s51, 4
	v_or_b32_e32 v43, s5, v98
	v_mov_b32_e32 v44, s4
	v_or_b32_e32 v47, 1, v40
	v_or_b32_e32 v48, 2, v40
	v_or_b32_e32 v49, 3, v40
	v_or_b32_e32 v50, s5, v107
	v_readlane_b32 s4, v255, 4
	v_mul_lo_u32 v41, v41, s53
	v_mul_lo_u32 v42, v42, s52
	v_mad_u32_u24 v45, v43, s53, v44
	v_mul_lo_u32 v46, v40, s52
	s_cmp_lt_i32 s51, s50
	v_mad_u32_u24 v44, v50, s53, v44
	v_lshl_add_u32 v51, v43, 1, s4
	v_cmp_gt_i32_e64 s[50:51], v43, v40
	v_cmp_gt_i32_e64 s[52:53], v43, v47
	v_cmp_gt_i32_e64 s[54:55], v43, v48
	v_cmp_gt_i32_e64 s[56:57], v43, v49
	v_lshl_add_u32 v43, v50, 1, s4
	s_cselect_b64 s[36:37], -1, 0
	v_cmp_gt_i32_e64 s[58:59], v50, v40
	v_cmp_gt_i32_e64 s[60:61], v50, v47
	v_cmp_gt_i32_e64 s[62:63], v50, v48
	v_cmp_gt_i32_e64 s[64:65], v50, v49
	v_add_u32_e32 v122, v45, v104
	v_add_u32_e32 v123, v51, v46
	v_add_u32_e32 v124, v44, v104
	v_add_u32_e32 v126, v43, v46
	v_add_u32_e32 v127, v155, v42
	v_add_u32_e32 v128, v156, v41
	s_waitcnt vmcnt(0)
	s_branch .LBB0_270

.LBB0_270:
	s_waitcnt vmcnt(4)
	ds_read_u16 v111, v246
	ds_read_u16 v116, v246 offset:128
	ds_read_u16 v118, v246 offset:256
	ds_read_u16 v120, v246 offset:384
	ds_read_u16 v125, v246 offset:512
	ds_read_u16 v130, v246 offset:640
	ds_read_u16 v132, v246 offset:768
	ds_read_u16 v134, v246 offset:896
	ds_read_u16 v135, v246 offset:1024
	ds_read_u16 v142, v246 offset:1152
	ds_read_u16 v144, v246 offset:1280
	ds_read_u16 v146, v246 offset:1408
	ds_read_u16 v148, v246 offset:1536
	ds_read_u16 v150, v246 offset:1664
	ds_read_u16 v168, v246 offset:1792
	ds_read_u16 v170, v246 offset:1920
	ds_read_u16 v212, v246 offset:2048
	ds_read_u16 v213, v246 offset:2176
	ds_read_u16 v214, v246 offset:2304
	ds_read_u16 v215, v246 offset:2432
	ds_read_u16 v216, v246 offset:2560
	ds_read_u16 v217, v246 offset:2688
	ds_read_u16 v218, v246 offset:2816
	ds_read_u16 v219, v246 offset:2944
	ds_read_u16 v220, v246 offset:3072
	ds_read_u16 v221, v246 offset:3200
	ds_read_u16 v222, v246 offset:3328
	ds_read_u16 v223, v246 offset:3456
	ds_read_u16 v224, v246 offset:3584
	ds_read_u16 v225, v246 offset:3712
	ds_read_u16 v226, v246 offset:3840
	ds_read_u16 v227, v246 offset:3968
	ds_read_u16 v115, v246 offset:4096
	ds_read_u16 v117, v246 offset:4224
	ds_read_u16 v119, v246 offset:4352
	ds_read_u16 v121, v246 offset:4480
	ds_read_u16 v129, v246 offset:4608
	ds_read_u16 v131, v246 offset:4736
	ds_read_u16 v133, v246 offset:4864
	ds_read_u16 v137, v246 offset:4992
	ds_read_u16 v136, v246 offset:5120
	ds_read_u16 v143, v246 offset:5248
	ds_read_u16 v145, v246 offset:5376
	ds_read_u16 v147, v246 offset:5504
	ds_read_u16 v149, v246 offset:5632
	ds_read_u16 v151, v246 offset:5760
	ds_read_u16 v169, v246 offset:5888
	ds_read_u16 v171, v246 offset:6016
	s_waitcnt lgkmcnt(15)
	v_lshlrev_b32_e32 v184, 16, v111
	v_lshlrev_b32_e32 v185, 16, v116
	v_lshlrev_b32_e32 v186, 16, v118
	v_lshlrev_b32_e32 v187, 16, v120
	v_lshlrev_b32_e32 v188, 16, v125
	v_lshlrev_b32_e32 v189, 16, v130
	v_lshlrev_b32_e32 v190, 16, v132
	v_lshlrev_b32_e32 v191, 16, v134
	v_lshlrev_b32_e32 v192, 16, v135
	v_lshlrev_b32_e32 v193, 16, v142
	v_lshlrev_b32_e32 v194, 16, v144
	v_lshlrev_b32_e32 v195, 16, v146
	v_lshlrev_b32_e32 v196, 16, v148
	v_lshlrev_b32_e32 v197, 16, v150
	v_lshlrev_b32_e32 v198, 16, v168
	v_lshlrev_b32_e32 v199, 16, v170
	v_add_f32_e32 v48, 0, v184
	v_add_f32_e32 v49, v48, v185
	v_add_f32_e32 v50, v49, v186
	v_add_f32_e32 v51, v50, v187
	v_add_f32_e32 v52, v51, v188
	v_add_f32_e32 v53, v52, v189
	v_add_f32_e32 v54, v53, v190
	v_add_f32_e32 v55, v54, v191
	v_add_f32_e32 v56, v55, v192
	v_add_f32_e32 v57, v56, v193
	v_add_f32_e32 v58, v57, v194
	v_add_f32_e32 v59, v58, v195
	v_add_f32_e32 v60, v59, v196
	v_add_f32_e32 v61, v60, v197
	v_add_f32_e32 v62, v61, v198
	v_add_f32_e32 v63, v62, v199
	ds_write_b32 v101, v63
	v_lshl_or_b32 v32, v213, 16, v212
	v_lshl_or_b32 v33, v215, 16, v214
	v_lshl_or_b32 v34, v217, 16, v216
	v_lshl_or_b32 v35, v219, 16, v218
	v_lshl_or_b32 v36, v221, 16, v220
	v_lshl_or_b32 v37, v223, 16, v222
	v_lshl_or_b32 v38, v225, 16, v224
	v_lshl_or_b32 v39, v227, 16, v226
	ds_write_b128 v160, v[32:35]
	ds_write_b128 v160, v[36:39] offset:16
	s_waitcnt lgkmcnt(0)
	s_barrier
	ds_read2st64_b32 v[42:43], v153 offset1:2
	ds_read2st64_b32 v[40:41], v153 offset0:4 offset1:6
	s_cmpk_eq_i32 s21, 0x3c0
	s_cbranch_scc1 .Lhg2_nopf
	s_add_i32 s4, s18, s21
	s_add_i32 s70, s4, 64
	s_and_b64 s[4:5], s[48:49], exec
	s_cselect_b32 s4, s70, s19
	s_ashr_i32 s5, s4, 31
	s_lshl_b64 s[70:71], s[4:5], 11
	s_add_u32 vcc_lo, s33, s70
	s_addc_u32 vcc_hi, s20, s71
	s_add_u32 s4, s25, s70
	s_addc_u32 s5, s10, s71
	s_add_u32 s70, s29, s70
	s_addc_u32 s71, s24, s71
	s_add_i32 m0, s100, 0
	s_nop 0
	global_load_lds_dwordx4 v244, s[4:5]
	s_add_i32 m0, s100, 1024
	s_nop 0
	global_load_lds_dwordx4 v245, s[4:5]
	s_add_i32 m0, s100, 2048
	s_nop 0
	global_load_lds_dwordx4 v244, s[70:71]
	s_add_i32 m0, s100, 3072
	s_nop 0
	global_load_lds_dwordx4 v245, s[70:71]
	s_add_i32 m0, s100, 4096
	s_nop 0
	global_load_lds_dwordx4 v244, vcc
	s_add_i32 m0, s100, 5120
	s_nop 0
	global_load_lds_dwordx4 v245, vcc
.Lhg2_nopf:
	s_waitcnt lgkmcnt(0)
	v_add_f32_e32 v46, v42, v43
	v_add_f32_e32 v45, v40, v41
	v_cndmask_b32_e64 v44, 0, v42, s[38:39]
	v_cndmask_b32_e64 v47, 0, v43, s[40:41]
	v_add_f32_e32 v44, v44, v47
	v_cndmask_b32_e64 v47, 0, v40, s[42:43]
	v_add_f32_e32 v44, v44, v47
	v_add_f32_e32 v138, v46, v45
	v_mul_f32_e32 v172, 0x3fb8aa3b, v46
	v_sub_f32_e32 v174, v138, v46
	v_mul_f32_e32 v173, 0x3fb8aa3b, v138
	v_exp_f32_e32 v172, v172
	v_mul_f32_e32 v174, 0x3fb8aa3b, v174
	v_exp_f32_e32 v173, v173
	v_exp_f32_e32 v174, v174
	s_and_b64 vcc, exec, s[44:45]
	s_cbranch_vccz .Lhg2_nodl
	ds_write_b32 v154, v173
.Lhg2_nodl:
	s_and_b64 vcc, exec, s[46:47]
	s_cbranch_vccz .Lhg2_blk1
	v_pk_add_f32 v[212:213], v[48:49], v[44:45] op_sel_hi:[1,0]
	v_pk_mul_f32 v[222:223], v[184:185], v[248:249]
	v_pk_mul_f32 v[214:215], v[212:213], v[248:249]
	v_pk_add_f32 v[220:221], v[46:47], v[212:213] op_sel_hi:[0,1] neg_lo:[0,1] neg_hi:[0,1]
	v_pk_mul_f32 v[220:221], v[220:221], v[248:249]
	v_exp_f32_e32 v222, v222
	v_exp_f32_e32 v223, v223
	v_min_f32_e64 v218, -v214, v247
	v_min_f32_e64 v219, -v215, v247
	v_exp_f32_e32 v216, v214
	v_exp_f32_e32 v217, v215
	v_exp_f32_e32 v218, v218
	v_exp_f32_e32 v219, v219
	v_exp_f32_e32 v220, v220
	v_exp_f32_e32 v221, v221
	v_pk_add_f32 v[222:223], v[238:239], v[222:223] neg_lo:[0,1] neg_hi:[0,1]
	v_lshlrev_b32_e32 v224, 16, v115
	v_lshlrev_b32_e32 v225, 16, v117
	v_pk_mul_f32 v[226:227], v[220:221], v[174:175] op_sel_hi:[1,0]
	v_pk_mul_f32 v[226:227], v[222:223], v[226:227]
	v_cvt_pk_bf16_f32 v32, v226, v227
	v_pk_mul_f32 v[224:225], v[224:225], v[216:217]
	v_cvt_pk_bf16_f32 v224, v224, v225
	v_pk_mul_f32 v[218:219], v[222:223], v[218:219]
	v_cvt_pk_bf16_f32 v218, v218, v219
	v_pk_mul_f32 v[220:221], v[222:223], v[220:221]
	v_cvt_pk_bf16_f32 v220, v220, v221
	ds_write_b16 v106, v224
	ds_write_b16_d16_hi v106, v224 offset:272
	ds_write_b16 v106, v218 offset:17408
	ds_write_b16_d16_hi v106, v218 offset:17680
	ds_write_b16 v106, v224 offset:34816
	ds_write_b16_d16_hi v106, v224 offset:35088
	ds_write_b16 v106, v220 offset:52224
	ds_write_b16_d16_hi v106, v220 offset:52496
	v_pk_add_f32 v[212:213], v[50:51], v[44:45] op_sel_hi:[1,0]
	v_pk_mul_f32 v[222:223], v[186:187], v[248:249]
	v_pk_mul_f32 v[214:215], v[212:213], v[248:249]
	v_pk_add_f32 v[220:221], v[46:47], v[212:213] op_sel_hi:[0,1] neg_lo:[0,1] neg_hi:[0,1]
	v_pk_mul_f32 v[220:221], v[220:221], v[248:249]
	v_exp_f32_e32 v222, v222
	v_exp_f32_e32 v223, v223
	v_min_f32_e64 v218, -v214, v247
	v_min_f32_e64 v219, -v215, v247
	v_exp_f32_e32 v216, v214
	v_exp_f32_e32 v217, v215
	v_exp_f32_e32 v218, v218
	v_exp_f32_e32 v219, v219
	v_exp_f32_e32 v220, v220
	v_exp_f32_e32 v221, v221
	v_pk_add_f32 v[222:223], v[238:239], v[222:223] neg_lo:[0,1] neg_hi:[0,1]
	v_lshlrev_b32_e32 v224, 16, v119
	v_lshlrev_b32_e32 v225, 16, v121
	v_pk_mul_f32 v[226:227], v[220:221], v[174:175] op_sel_hi:[1,0]
	v_pk_mul_f32 v[226:227], v[222:223], v[226:227]
	v_cvt_pk_bf16_f32 v33, v226, v227
	v_pk_mul_f32 v[224:225], v[224:225], v[216:217]
	v_cvt_pk_bf16_f32 v224, v224, v225
	v_pk_mul_f32 v[218:219], v[222:223], v[218:219]
	v_cvt_pk_bf16_f32 v218, v218, v219
	v_pk_mul_f32 v[220:221], v[222:223], v[220:221]
	v_cvt_pk_bf16_f32 v220, v220, v221
	ds_write_b16 v106, v224 offset:544
	ds_write_b16_d16_hi v106, v224 offset:816
	ds_write_b16 v106, v218 offset:17952
	ds_write_b16_d16_hi v106, v218 offset:18224
	ds_write_b16 v106, v224 offset:35360
	ds_write_b16_d16_hi v106, v224 offset:35632
	ds_write_b16 v106, v220 offset:52768
	ds_write_b16_d16_hi v106, v220 offset:53040
	v_pk_add_f32 v[212:213], v[52:53], v[44:45] op_sel_hi:[1,0]
	v_pk_mul_f32 v[222:223], v[188:189], v[248:249]
	v_pk_mul_f32 v[214:215], v[212:213], v[248:249]
	v_pk_add_f32 v[220:221], v[46:47], v[212:213] op_sel_hi:[0,1] neg_lo:[0,1] neg_hi:[0,1]
	v_pk_mul_f32 v[220:221], v[220:221], v[248:249]
	v_exp_f32_e32 v222, v222
	v_exp_f32_e32 v223, v223
	v_min_f32_e64 v218, -v214, v247
	v_min_f32_e64 v219, -v215, v247
	v_exp_f32_e32 v216, v214
	v_exp_f32_e32 v217, v215
	v_exp_f32_e32 v218, v218
	v_exp_f32_e32 v219, v219
	v_exp_f32_e32 v220, v220
	v_exp_f32_e32 v221, v221
	v_pk_add_f32 v[222:223], v[238:239], v[222:223] neg_lo:[0,1] neg_hi:[0,1]
	v_lshlrev_b32_e32 v224, 16, v129
	v_lshlrev_b32_e32 v225, 16, v131
	v_pk_mul_f32 v[226:227], v[220:221], v[174:175] op_sel_hi:[1,0]
	v_pk_mul_f32 v[226:227], v[222:223], v[226:227]
	v_cvt_pk_bf16_f32 v34, v226, v227
	v_pk_mul_f32 v[224:225], v[224:225], v[216:217]
	v_cvt_pk_bf16_f32 v224, v224, v225
	v_pk_mul_f32 v[218:219], v[222:223], v[218:219]
	v_cvt_pk_bf16_f32 v218, v218, v219
	v_pk_mul_f32 v[220:221], v[222:223], v[220:221]
	v_cvt_pk_bf16_f32 v220, v220, v221
	ds_write_b16 v106, v224 offset:1088
	ds_write_b16_d16_hi v106, v224 offset:1360
	ds_write_b16 v106, v218 offset:18496
	ds_write_b16_d16_hi v106, v218 offset:18768
	ds_write_b16 v106, v224 offset:35904
	ds_write_b16_d16_hi v106, v224 offset:36176
	ds_write_b16 v106, v220 offset:53312
	ds_write_b16_d16_hi v106, v220 offset:53584
	v_pk_add_f32 v[212:213], v[54:55], v[44:45] op_sel_hi:[1,0]
	v_pk_mul_f32 v[222:223], v[190:191], v[248:249]
	v_pk_mul_f32 v[214:215], v[212:213], v[248:249]
	v_pk_add_f32 v[220:221], v[46:47], v[212:213] op_sel_hi:[0,1] neg_lo:[0,1] neg_hi:[0,1]
	v_pk_mul_f32 v[220:221], v[220:221], v[248:249]
	v_exp_f32_e32 v222, v222
	v_exp_f32_e32 v223, v223
	v_min_f32_e64 v218, -v214, v247
	v_min_f32_e64 v219, -v215, v247
	v_exp_f32_e32 v216, v214
	v_exp_f32_e32 v217, v215
	v_exp_f32_e32 v218, v218
	v_exp_f32_e32 v219, v219
	v_exp_f32_e32 v220, v220
	v_exp_f32_e32 v221, v221
	v_pk_add_f32 v[222:223], v[238:239], v[222:223] neg_lo:[0,1] neg_hi:[0,1]
	v_lshlrev_b32_e32 v224, 16, v133
	v_lshlrev_b32_e32 v225, 16, v137
	v_pk_mul_f32 v[226:227], v[220:221], v[174:175] op_sel_hi:[1,0]
	v_pk_mul_f32 v[226:227], v[222:223], v[226:227]
	v_cvt_pk_bf16_f32 v35, v226, v227
	v_pk_mul_f32 v[224:225], v[224:225], v[216:217]
	v_cvt_pk_bf16_f32 v224, v224, v225
	v_pk_mul_f32 v[218:219], v[222:223], v[218:219]
	v_cvt_pk_bf16_f32 v218, v218, v219
	v_pk_mul_f32 v[220:221], v[222:223], v[220:221]
	v_cvt_pk_bf16_f32 v220, v220, v221
	ds_write_b16 v106, v224 offset:1632
	ds_write_b16_d16_hi v106, v224 offset:1904
	ds_write_b16 v106, v218 offset:19040
	ds_write_b16_d16_hi v106, v218 offset:19312
	ds_write_b16 v106, v224 offset:36448
	ds_write_b16_d16_hi v106, v224 offset:36720
	ds_write_b16 v106, v220 offset:53856
	ds_write_b16_d16_hi v106, v220 offset:54128
	v_pk_add_f32 v[212:213], v[56:57], v[44:45] op_sel_hi:[1,0]
	v_pk_mul_f32 v[222:223], v[192:193], v[248:249]
	v_pk_mul_f32 v[214:215], v[212:213], v[248:249]
	v_pk_add_f32 v[220:221], v[46:47], v[212:213] op_sel_hi:[0,1] neg_lo:[0,1] neg_hi:[0,1]
	v_pk_mul_f32 v[220:221], v[220:221], v[248:249]
	v_exp_f32_e32 v222, v222
	v_exp_f32_e32 v223, v223
	v_min_f32_e64 v218, -v214, v247
	v_min_f32_e64 v219, -v215, v247
	v_exp_f32_e32 v216, v214
	v_exp_f32_e32 v217, v215
	v_exp_f32_e32 v218, v218
	v_exp_f32_e32 v219, v219
	v_exp_f32_e32 v220, v220
	v_exp_f32_e32 v221, v221
	v_pk_add_f32 v[222:223], v[238:239], v[222:223] neg_lo:[0,1] neg_hi:[0,1]
	v_lshlrev_b32_e32 v224, 16, v136
	v_lshlrev_b32_e32 v225, 16, v143
	v_pk_mul_f32 v[226:227], v[220:221], v[174:175] op_sel_hi:[1,0]
	v_pk_mul_f32 v[226:227], v[222:223], v[226:227]
	v_cvt_pk_bf16_f32 v36, v226, v227
	v_pk_mul_f32 v[224:225], v[224:225], v[216:217]
	v_cvt_pk_bf16_f32 v224, v224, v225
	v_pk_mul_f32 v[218:219], v[222:223], v[218:219]
	v_cvt_pk_bf16_f32 v218, v218, v219
	v_pk_mul_f32 v[220:221], v[222:223], v[220:221]
	v_cvt_pk_bf16_f32 v220, v220, v221
	ds_write_b16 v106, v224 offset:2176
	ds_write_b16_d16_hi v106, v224 offset:2448
	ds_write_b16 v106, v218 offset:19584
	ds_write_b16_d16_hi v106, v218 offset:19856
	ds_write_b16 v106, v224 offset:36992
	ds_write_b16_d16_hi v106, v224 offset:37264
	ds_write_b16 v106, v220 offset:54400
	ds_write_b16_d16_hi v106, v220 offset:54672
	v_pk_add_f32 v[212:213], v[58:59], v[44:45] op_sel_hi:[1,0]
	v_pk_mul_f32 v[222:223], v[194:195], v[248:249]
	v_pk_mul_f32 v[214:215], v[212:213], v[248:249]
	v_pk_add_f32 v[220:221], v[46:47], v[212:213] op_sel_hi:[0,1] neg_lo:[0,1] neg_hi:[0,1]
	v_pk_mul_f32 v[220:221], v[220:221], v[248:249]
	v_exp_f32_e32 v222, v222
	v_exp_f32_e32 v223, v223
	v_min_f32_e64 v218, -v214, v247
	v_min_f32_e64 v219, -v215, v247
	v_exp_f32_e32 v216, v214
	v_exp_f32_e32 v217, v215
	v_exp_f32_e32 v218, v218
	v_exp_f32_e32 v219, v219
	v_exp_f32_e32 v220, v220
	v_exp_f32_e32 v221, v221
	v_pk_add_f32 v[222:223], v[238:239], v[222:223] neg_lo:[0,1] neg_hi:[0,1]
	v_lshlrev_b32_e32 v224, 16, v145
	v_lshlrev_b32_e32 v225, 16, v147
	v_pk_mul_f32 v[226:227], v[220:221], v[174:175] op_sel_hi:[1,0]
	v_pk_mul_f32 v[226:227], v[222:223], v[226:227]
	v_cvt_pk_bf16_f32 v37, v226, v227
	v_pk_mul_f32 v[224:225], v[224:225], v[216:217]
	v_cvt_pk_bf16_f32 v224, v224, v225
	v_pk_mul_f32 v[218:219], v[222:223], v[218:219]
	v_cvt_pk_bf16_f32 v218, v218, v219
	v_pk_mul_f32 v[220:221], v[222:223], v[220:221]
	v_cvt_pk_bf16_f32 v220, v220, v221
	ds_write_b16 v106, v224 offset:2720
	ds_write_b16_d16_hi v106, v224 offset:2992
	ds_write_b16 v106, v218 offset:20128
	ds_write_b16_d16_hi v106, v218 offset:20400
	ds_write_b16 v106, v224 offset:37536
	ds_write_b16_d16_hi v106, v224 offset:37808
	ds_write_b16 v106, v220 offset:54944
	ds_write_b16_d16_hi v106, v220 offset:55216
	v_pk_add_f32 v[212:213], v[60:61], v[44:45] op_sel_hi:[1,0]
	v_pk_mul_f32 v[222:223], v[196:197], v[248:249]
	v_pk_mul_f32 v[214:215], v[212:213], v[248:249]
	v_pk_add_f32 v[220:221], v[46:47], v[212:213] op_sel_hi:[0,1] neg_lo:[0,1] neg_hi:[0,1]
	v_pk_mul_f32 v[220:221], v[220:221], v[248:249]
	v_exp_f32_e32 v222, v222
	v_exp_f32_e32 v223, v223
	v_min_f32_e64 v218, -v214, v247
	v_min_f32_e64 v219, -v215, v247
	v_exp_f32_e32 v216, v214
	v_exp_f32_e32 v217, v215
	v_exp_f32_e32 v218, v218
	v_exp_f32_e32 v219, v219
	v_exp_f32_e32 v220, v220
	v_exp_f32_e32 v221, v221
	v_pk_add_f32 v[222:223], v[238:239], v[222:223] neg_lo:[0,1] neg_hi:[0,1]
	v_lshlrev_b32_e32 v224, 16, v149
	v_lshlrev_b32_e32 v225, 16, v151
	v_pk_mul_f32 v[226:227], v[220:221], v[174:175] op_sel_hi:[1,0]
	v_pk_mul_f32 v[226:227], v[222:223], v[226:227]
	v_cvt_pk_bf16_f32 v38, v226, v227
	v_pk_mul_f32 v[224:225], v[224:225], v[216:217]
	v_cvt_pk_bf16_f32 v224, v224, v225
	v_pk_mul_f32 v[218:219], v[222:223], v[218:219]
	v_cvt_pk_bf16_f32 v218, v218, v219
	v_pk_mul_f32 v[220:221], v[222:223], v[220:221]
	v_cvt_pk_bf16_f32 v220, v220, v221
	ds_write_b16 v106, v224 offset:3264
	ds_write_b16_d16_hi v106, v224 offset:3536
	ds_write_b16 v106, v218 offset:20672
	ds_write_b16_d16_hi v106, v218 offset:20944
	ds_write_b16 v106, v224 offset:38080
	ds_write_b16_d16_hi v106, v224 offset:38352
	ds_write_b16 v106, v220 offset:55488
	ds_write_b16_d16_hi v106, v220 offset:55760
	v_pk_add_f32 v[212:213], v[62:63], v[44:45] op_sel_hi:[1,0]
	v_pk_mul_f32 v[222:223], v[198:199], v[248:249]
	v_pk_mul_f32 v[214:215], v[212:213], v[248:249]
	v_pk_add_f32 v[220:221], v[46:47], v[212:213] op_sel_hi:[0,1] neg_lo:[0,1] neg_hi:[0,1]
	v_pk_mul_f32 v[220:221], v[220:221], v[248:249]
	v_exp_f32_e32 v222, v222
	v_exp_f32_e32 v223, v223
	v_min_f32_e64 v218, -v214, v247
	v_min_f32_e64 v219, -v215, v247
	v_exp_f32_e32 v216, v214
	v_exp_f32_e32 v217, v215
	v_exp_f32_e32 v218, v218
	v_exp_f32_e32 v219, v219
	v_exp_f32_e32 v220, v220
	v_exp_f32_e32 v221, v221
	v_pk_add_f32 v[222:223], v[238:239], v[222:223] neg_lo:[0,1] neg_hi:[0,1]
	v_lshlrev_b32_e32 v224, 16, v169
	v_lshlrev_b32_e32 v225, 16, v171
	v_pk_mul_f32 v[226:227], v[220:221], v[174:175] op_sel_hi:[1,0]
	v_pk_mul_f32 v[226:227], v[222:223], v[226:227]
	v_cvt_pk_bf16_f32 v39, v226, v227
	v_pk_mul_f32 v[224:225], v[224:225], v[216:217]
	v_cvt_pk_bf16_f32 v224, v224, v225
	v_pk_mul_f32 v[218:219], v[222:223], v[218:219]
	v_cvt_pk_bf16_f32 v218, v218, v219
	v_pk_mul_f32 v[220:221], v[222:223], v[220:221]
	v_cvt_pk_bf16_f32 v220, v220, v221
	ds_write_b16 v106, v224 offset:3808
	ds_write_b16_d16_hi v106, v224 offset:4080
	ds_write_b16 v106, v218 offset:21216
	ds_write_b16_d16_hi v106, v218 offset:21488
	ds_write_b16 v106, v224 offset:38624
	ds_write_b16_d16_hi v106, v224 offset:38896
	ds_write_b16 v106, v220 offset:56032
	ds_write_b16_d16_hi v106, v220 offset:56304
	s_branch .Lhg2_kst
.Lhg2_blk1:
	v_pk_add_f32 v[212:213], v[48:49], v[44:45] op_sel_hi:[1,0]
	v_pk_mul_f32 v[222:223], v[184:185], v[248:249]
	v_pk_add_f32 v[214:215], v[212:213], v[46:47] op_sel_hi:[1,0] neg_lo:[0,1] neg_hi:[0,1]
	v_pk_mul_f32 v[214:215], v[214:215], v[248:249]
	v_pk_add_f32 v[220:221], v[138:139], v[212:213] op_sel_hi:[0,1] neg_lo:[0,1] neg_hi:[0,1]
	v_pk_mul_f32 v[220:221], v[220:221], v[248:249]
	v_exp_f32_e32 v222, v222
	v_exp_f32_e32 v223, v223
	v_min_f32_e64 v218, -v214, v247
	v_min_f32_e64 v219, -v215, v247
	v_exp_f32_e32 v216, v214
	v_exp_f32_e32 v217, v215
	v_exp_f32_e32 v218, v218
	v_exp_f32_e32 v219, v219
	v_exp_f32_e32 v220, v220
	v_exp_f32_e32 v221, v221
	v_pk_add_f32 v[222:223], v[238:239], v[222:223] neg_lo:[0,1] neg_hi:[0,1]
	v_lshlrev_b32_e32 v224, 16, v115
	v_lshlrev_b32_e32 v225, 16, v117
	v_pk_mul_f32 v[226:227], v[222:223], v[220:221]
	v_cvt_pk_bf16_f32 v32, v226, v227
	v_pk_mul_f32 v[224:225], v[224:225], v[216:217]
	v_pk_mul_f32 v[226:227], v[224:225], v[172:173] op_sel_hi:[1,0]
	v_cvt_pk_bf16_f32 v224, v224, v225
	v_cvt_pk_bf16_f32 v226, v226, v227
	v_pk_mul_f32 v[218:219], v[222:223], v[218:219]
	v_cvt_pk_bf16_f32 v218, v218, v219
	ds_write_b16 v106, v224
	ds_write_b16_d16_hi v106, v224 offset:272
	ds_write_b16 v106, v218 offset:17408
	ds_write_b16_d16_hi v106, v218 offset:17680
	ds_write_b16 v106, v226 offset:34816
	ds_write_b16_d16_hi v106, v226 offset:35088
	v_pk_add_f32 v[212:213], v[50:51], v[44:45] op_sel_hi:[1,0]
	v_pk_mul_f32 v[222:223], v[186:187], v[248:249]
	v_pk_add_f32 v[214:215], v[212:213], v[46:47] op_sel_hi:[1,0] neg_lo:[0,1] neg_hi:[0,1]
	v_pk_mul_f32 v[214:215], v[214:215], v[248:249]
	v_pk_add_f32 v[220:221], v[138:139], v[212:213] op_sel_hi:[0,1] neg_lo:[0,1] neg_hi:[0,1]
	v_pk_mul_f32 v[220:221], v[220:221], v[248:249]
	v_exp_f32_e32 v222, v222
	v_exp_f32_e32 v223, v223
	v_min_f32_e64 v218, -v214, v247
	v_min_f32_e64 v219, -v215, v247
	v_exp_f32_e32 v216, v214
	v_exp_f32_e32 v217, v215
	v_exp_f32_e32 v218, v218
	v_exp_f32_e32 v219, v219
	v_exp_f32_e32 v220, v220
	v_exp_f32_e32 v221, v221
	v_pk_add_f32 v[222:223], v[238:239], v[222:223] neg_lo:[0,1] neg_hi:[0,1]
	v_lshlrev_b32_e32 v224, 16, v119
	v_lshlrev_b32_e32 v225, 16, v121
	v_pk_mul_f32 v[226:227], v[222:223], v[220:221]
	v_cvt_pk_bf16_f32 v33, v226, v227
	v_pk_mul_f32 v[224:225], v[224:225], v[216:217]
	v_pk_mul_f32 v[226:227], v[224:225], v[172:173] op_sel_hi:[1,0]
	v_cvt_pk_bf16_f32 v224, v224, v225
	v_cvt_pk_bf16_f32 v226, v226, v227
	v_pk_mul_f32 v[218:219], v[222:223], v[218:219]
	v_cvt_pk_bf16_f32 v218, v218, v219
	ds_write_b16 v106, v224 offset:544
	ds_write_b16_d16_hi v106, v224 offset:816
	ds_write_b16 v106, v218 offset:17952
	ds_write_b16_d16_hi v106, v218 offset:18224
	ds_write_b16 v106, v226 offset:35360
	ds_write_b16_d16_hi v106, v226 offset:35632
	v_pk_add_f32 v[212:213], v[52:53], v[44:45] op_sel_hi:[1,0]
	v_pk_mul_f32 v[222:223], v[188:189], v[248:249]
	v_pk_add_f32 v[214:215], v[212:213], v[46:47] op_sel_hi:[1,0] neg_lo:[0,1] neg_hi:[0,1]
	v_pk_mul_f32 v[214:215], v[214:215], v[248:249]
	v_pk_add_f32 v[220:221], v[138:139], v[212:213] op_sel_hi:[0,1] neg_lo:[0,1] neg_hi:[0,1]
	v_pk_mul_f32 v[220:221], v[220:221], v[248:249]
	v_exp_f32_e32 v222, v222
	v_exp_f32_e32 v223, v223
	v_min_f32_e64 v218, -v214, v247
	v_min_f32_e64 v219, -v215, v247
	v_exp_f32_e32 v216, v214
	v_exp_f32_e32 v217, v215
	v_exp_f32_e32 v218, v218
	v_exp_f32_e32 v219, v219
	v_exp_f32_e32 v220, v220
	v_exp_f32_e32 v221, v221
	v_pk_add_f32 v[222:223], v[238:239], v[222:223] neg_lo:[0,1] neg_hi:[0,1]
	v_lshlrev_b32_e32 v224, 16, v129
	v_lshlrev_b32_e32 v225, 16, v131
	v_pk_mul_f32 v[226:227], v[222:223], v[220:221]
	v_cvt_pk_bf16_f32 v34, v226, v227
	v_pk_mul_f32 v[224:225], v[224:225], v[216:217]
	v_pk_mul_f32 v[226:227], v[224:225], v[172:173] op_sel_hi:[1,0]
	v_cvt_pk_bf16_f32 v224, v224, v225
	v_cvt_pk_bf16_f32 v226, v226, v227
	v_pk_mul_f32 v[218:219], v[222:223], v[218:219]
	v_cvt_pk_bf16_f32 v218, v218, v219
	ds_write_b16 v106, v224 offset:1088
	ds_write_b16_d16_hi v106, v224 offset:1360
	ds_write_b16 v106, v218 offset:18496
	ds_write_b16_d16_hi v106, v218 offset:18768
	ds_write_b16 v106, v226 offset:35904
	ds_write_b16_d16_hi v106, v226 offset:36176
	v_pk_add_f32 v[212:213], v[54:55], v[44:45] op_sel_hi:[1,0]
	v_pk_mul_f32 v[222:223], v[190:191], v[248:249]
	v_pk_add_f32 v[214:215], v[212:213], v[46:47] op_sel_hi:[1,0] neg_lo:[0,1] neg_hi:[0,1]
	v_pk_mul_f32 v[214:215], v[214:215], v[248:249]
	v_pk_add_f32 v[220:221], v[138:139], v[212:213] op_sel_hi:[0,1] neg_lo:[0,1] neg_hi:[0,1]
	v_pk_mul_f32 v[220:221], v[220:221], v[248:249]
	v_exp_f32_e32 v222, v222
	v_exp_f32_e32 v223, v223
	v_min_f32_e64 v218, -v214, v247
	v_min_f32_e64 v219, -v215, v247
	v_exp_f32_e32 v216, v214
	v_exp_f32_e32 v217, v215
	v_exp_f32_e32 v218, v218
	v_exp_f32_e32 v219, v219
	v_exp_f32_e32 v220, v220
	v_exp_f32_e32 v221, v221
	v_pk_add_f32 v[222:223], v[238:239], v[222:223] neg_lo:[0,1] neg_hi:[0,1]
	v_lshlrev_b32_e32 v224, 16, v133
	v_lshlrev_b32_e32 v225, 16, v137
	v_pk_mul_f32 v[226:227], v[222:223], v[220:221]
	v_cvt_pk_bf16_f32 v35, v226, v227
	v_pk_mul_f32 v[224:225], v[224:225], v[216:217]
	v_pk_mul_f32 v[226:227], v[224:225], v[172:173] op_sel_hi:[1,0]
	v_cvt_pk_bf16_f32 v224, v224, v225
	v_cvt_pk_bf16_f32 v226, v226, v227
	v_pk_mul_f32 v[218:219], v[222:223], v[218:219]
	v_cvt_pk_bf16_f32 v218, v218, v219
	ds_write_b16 v106, v224 offset:1632
	ds_write_b16_d16_hi v106, v224 offset:1904
	ds_write_b16 v106, v218 offset:19040
	ds_write_b16_d16_hi v106, v218 offset:19312
	ds_write_b16 v106, v226 offset:36448
	ds_write_b16_d16_hi v106, v226 offset:36720
	v_pk_add_f32 v[212:213], v[56:57], v[44:45] op_sel_hi:[1,0]
	v_pk_mul_f32 v[222:223], v[192:193], v[248:249]
	v_pk_add_f32 v[214:215], v[212:213], v[46:47] op_sel_hi:[1,0] neg_lo:[0,1] neg_hi:[0,1]
	v_pk_mul_f32 v[214:215], v[214:215], v[248:249]
	v_pk_add_f32 v[220:221], v[138:139], v[212:213] op_sel_hi:[0,1] neg_lo:[0,1] neg_hi:[0,1]
	v_pk_mul_f32 v[220:221], v[220:221], v[248:249]
	v_exp_f32_e32 v222, v222
	v_exp_f32_e32 v223, v223
	v_min_f32_e64 v218, -v214, v247
	v_min_f32_e64 v219, -v215, v247
	v_exp_f32_e32 v216, v214
	v_exp_f32_e32 v217, v215
	v_exp_f32_e32 v218, v218
	v_exp_f32_e32 v219, v219
	v_exp_f32_e32 v220, v220
	v_exp_f32_e32 v221, v221
	v_pk_add_f32 v[222:223], v[238:239], v[222:223] neg_lo:[0,1] neg_hi:[0,1]
	v_lshlrev_b32_e32 v224, 16, v136
	v_lshlrev_b32_e32 v225, 16, v143
	v_pk_mul_f32 v[226:227], v[222:223], v[220:221]
	v_cvt_pk_bf16_f32 v36, v226, v227
	v_pk_mul_f32 v[224:225], v[224:225], v[216:217]
	v_pk_mul_f32 v[226:227], v[224:225], v[172:173] op_sel_hi:[1,0]
	v_cvt_pk_bf16_f32 v224, v224, v225
	v_cvt_pk_bf16_f32 v226, v226, v227
	v_pk_mul_f32 v[218:219], v[222:223], v[218:219]
	v_cvt_pk_bf16_f32 v218, v218, v219
	ds_write_b16 v106, v224 offset:2176
	ds_write_b16_d16_hi v106, v224 offset:2448
	ds_write_b16 v106, v218 offset:19584
	ds_write_b16_d16_hi v106, v218 offset:19856
	ds_write_b16 v106, v226 offset:36992
	ds_write_b16_d16_hi v106, v226 offset:37264
	v_pk_add_f32 v[212:213], v[58:59], v[44:45] op_sel_hi:[1,0]
	v_pk_mul_f32 v[222:223], v[194:195], v[248:249]
	v_pk_add_f32 v[214:215], v[212:213], v[46:47] op_sel_hi:[1,0] neg_lo:[0,1] neg_hi:[0,1]
	v_pk_mul_f32 v[214:215], v[214:215], v[248:249]
	v_pk_add_f32 v[220:221], v[138:139], v[212:213] op_sel_hi:[0,1] neg_lo:[0,1] neg_hi:[0,1]
	v_pk_mul_f32 v[220:221], v[220:221], v[248:249]
	v_exp_f32_e32 v222, v222
	v_exp_f32_e32 v223, v223
	v_min_f32_e64 v218, -v214, v247
	v_min_f32_e64 v219, -v215, v247
	v_exp_f32_e32 v216, v214
	v_exp_f32_e32 v217, v215
	v_exp_f32_e32 v218, v218
	v_exp_f32_e32 v219, v219
	v_exp_f32_e32 v220, v220
	v_exp_f32_e32 v221, v221
	v_pk_add_f32 v[222:223], v[238:239], v[222:223] neg_lo:[0,1] neg_hi:[0,1]
	v_lshlrev_b32_e32 v224, 16, v145
	v_lshlrev_b32_e32 v225, 16, v147
	v_pk_mul_f32 v[226:227], v[222:223], v[220:221]
	v_cvt_pk_bf16_f32 v37, v226, v227
	v_pk_mul_f32 v[224:225], v[224:225], v[216:217]
	v_pk_mul_f32 v[226:227], v[224:225], v[172:173] op_sel_hi:[1,0]
	v_cvt_pk_bf16_f32 v224, v224, v225
	v_cvt_pk_bf16_f32 v226, v226, v227
	v_pk_mul_f32 v[218:219], v[222:223], v[218:219]
	v_cvt_pk_bf16_f32 v218, v218, v219
	ds_write_b16 v106, v224 offset:2720
	ds_write_b16_d16_hi v106, v224 offset:2992
	ds_write_b16 v106, v218 offset:20128
	ds_write_b16_d16_hi v106, v218 offset:20400
	ds_write_b16 v106, v226 offset:37536
	ds_write_b16_d16_hi v106, v226 offset:37808
	v_pk_add_f32 v[212:213], v[60:61], v[44:45] op_sel_hi:[1,0]
	v_pk_mul_f32 v[222:223], v[196:197], v[248:249]
	v_pk_add_f32 v[214:215], v[212:213], v[46:47] op_sel_hi:[1,0] neg_lo:[0,1] neg_hi:[0,1]
	v_pk_mul_f32 v[214:215], v[214:215], v[248:249]
	v_pk_add_f32 v[220:221], v[138:139], v[212:213] op_sel_hi:[0,1] neg_lo:[0,1] neg_hi:[0,1]
	v_pk_mul_f32 v[220:221], v[220:221], v[248:249]
	v_exp_f32_e32 v222, v222
	v_exp_f32_e32 v223, v223
	v_min_f32_e64 v218, -v214, v247
	v_min_f32_e64 v219, -v215, v247
	v_exp_f32_e32 v216, v214
	v_exp_f32_e32 v217, v215
	v_exp_f32_e32 v218, v218
	v_exp_f32_e32 v219, v219
	v_exp_f32_e32 v220, v220
	v_exp_f32_e32 v221, v221
	v_pk_add_f32 v[222:223], v[238:239], v[222:223] neg_lo:[0,1] neg_hi:[0,1]
	v_lshlrev_b32_e32 v224, 16, v149
	v_lshlrev_b32_e32 v225, 16, v151
	v_pk_mul_f32 v[226:227], v[222:223], v[220:221]
	v_cvt_pk_bf16_f32 v38, v226, v227
	v_pk_mul_f32 v[224:225], v[224:225], v[216:217]
	v_pk_mul_f32 v[226:227], v[224:225], v[172:173] op_sel_hi:[1,0]
	v_cvt_pk_bf16_f32 v224, v224, v225
	v_cvt_pk_bf16_f32 v226, v226, v227
	v_pk_mul_f32 v[218:219], v[222:223], v[218:219]
	v_cvt_pk_bf16_f32 v218, v218, v219
	ds_write_b16 v106, v224 offset:3264
	ds_write_b16_d16_hi v106, v224 offset:3536
	ds_write_b16 v106, v218 offset:20672
	ds_write_b16_d16_hi v106, v218 offset:20944
	ds_write_b16 v106, v226 offset:38080
	ds_write_b16_d16_hi v106, v226 offset:38352
	v_pk_add_f32 v[212:213], v[62:63], v[44:45] op_sel_hi:[1,0]
	v_pk_mul_f32 v[222:223], v[198:199], v[248:249]
	v_pk_add_f32 v[214:215], v[212:213], v[46:47] op_sel_hi:[1,0] neg_lo:[0,1] neg_hi:[0,1]
	v_pk_mul_f32 v[214:215], v[214:215], v[248:249]
	v_pk_add_f32 v[220:221], v[138:139], v[212:213] op_sel_hi:[0,1] neg_lo:[0,1] neg_hi:[0,1]
	v_pk_mul_f32 v[220:221], v[220:221], v[248:249]
	v_exp_f32_e32 v222, v222
	v_exp_f32_e32 v223, v223
	v_min_f32_e64 v218, -v214, v247
	v_min_f32_e64 v219, -v215, v247
	v_exp_f32_e32 v216, v214
	v_exp_f32_e32 v217, v215
	v_exp_f32_e32 v218, v218
	v_exp_f32_e32 v219, v219
	v_exp_f32_e32 v220, v220
	v_exp_f32_e32 v221, v221
	v_pk_add_f32 v[222:223], v[238:239], v[222:223] neg_lo:[0,1] neg_hi:[0,1]
	v_lshlrev_b32_e32 v224, 16, v169
	v_lshlrev_b32_e32 v225, 16, v171
	v_pk_mul_f32 v[226:227], v[222:223], v[220:221]
	v_cvt_pk_bf16_f32 v39, v226, v227
	v_pk_mul_f32 v[224:225], v[224:225], v[216:217]
	v_pk_mul_f32 v[226:227], v[224:225], v[172:173] op_sel_hi:[1,0]
	v_cvt_pk_bf16_f32 v224, v224, v225
	v_cvt_pk_bf16_f32 v226, v226, v227
	v_pk_mul_f32 v[218:219], v[222:223], v[218:219]
	v_cvt_pk_bf16_f32 v218, v218, v219
	ds_write_b16 v106, v224 offset:3808
	ds_write_b16_d16_hi v106, v224 offset:4080
	ds_write_b16 v106, v218 offset:21216
	ds_write_b16_d16_hi v106, v218 offset:21488
	ds_write_b16 v106, v226 offset:38624
	ds_write_b16_d16_hi v106, v226 offset:38896
.Lhg2_kst:
	ds_write_b128 v161, v[32:35] offset:60928
	ds_write_b128 v161, v[36:39] offset:60944
	s_waitcnt lgkmcnt(0)
	s_barrier

.Lepi_tD:
	s_lshl_b32 s4, s4, 1
	s_add_u32 s5, s5, s4
	s_add_u32 s8, s90, 0x7000000
	s_addc_u32 s9, s91, 0
	s_add_u32 s8, s8, s5
	s_addc_u32 s9, s9, 0
	s_lshl_b32 s20, 16, s10
	s_mul_i32 s36, s20, 5
	s_lshl_b32 s18, s3, 8
	s_lshl_b32 s19, s1, 6
	s_add_u32 s18, s18, s19
	v_add_u32_e32 v157, s18, v131
	v_lshlrev_b32_e32 v157, s10, v157
	v_lshl_add_u32 v157, v132, 4, v157
	s_lshl_b32 s19, s0, 6
	v_add_u32_e32 v157, s19, v157
	v_mov_b32_e32 v167, v157
	s_mov_b32 s56, 0xbfb8aa3b
	s_mov_b32 s57, 0xbfb8aa3b
	s_mov_b32 s58, 1.0
	s_mov_b32 s59, 1.0
	s_cmp_eq_u32 s37, 0
	s_cbranch_scc1 .Lepi_silu
	s_cmp_eq_u32 s37, 1
	s_cbranch_scc1 .Lepi_log
	s_cmp_eq_u32 s37, 3
	s_cbranch_scc1 .Lepi_sig
	s_cmp_eq_u32 s37, 2
	s_cbranch_scc1 .Lepi_copy
	s_and_b32 s4, s3, 31
	s_lshl_b32 s4, s4, 8
	s_lshl_b32 s5, s1, 6
	s_add_u32 s4, s4, s5
	v_add_u32_e32 v166, s4, v131
	v_lshlrev_b32_e32 v166, 7, v166
	v_and_b32_e32 v139, 1, v132
	v_lshl_add_u32 v166, v139, 6, v166
	s_add_u32 s54, s90, 0x3410000
	s_addc_u32 s55, s91, 0
	v_xor_b32_e32 v167, 32, v130
	v_lshlrev_b32_e32 v167, 2, v167
	v_cmp_gt_u32_e32 vcc, 2, v132
	s_nop 1
	v_cndmask_b32_e64 v138, 1.0, -1.0, vcc
	s_mov_b32 s2, 0x3e0293ee
	s_mov_b32 s3, 0x3e0293ee
	s_cmp_lg_u32 s0, 0
	s_cbranch_scc1 .Lepi_rot_plain
	global_load_dwordx4 v[130:133], v166, s[54:55]
	global_load_dwordx4 v[134:137], v166, s[54:55] offset:16
	global_load_dwordx4 v[196:199], v166, s[54:55] offset:32
	global_load_dwordx4 v[158:161], v166, s[54:55] offset:48
	s_waitcnt vmcnt(0)
	v_mul_f32_e32 v131, v138, v131
	v_mul_f32_e32 v133, v138, v133
	v_mul_f32_e32 v135, v138, v135
	v_mul_f32_e32 v137, v138, v137
	v_mul_f32_e32 v197, v138, v197
	v_mul_f32_e32 v199, v138, v199
	v_mul_f32_e32 v159, v138, v159
	v_mul_f32_e32 v161, v138, v161
	ds_bpermute_b32 v162, v167, v126
	ds_bpermute_b32 v163, v167, v127
	ds_bpermute_b32 v164, v167, v128
	ds_bpermute_b32 v165, v167, v129
	v_mul_f32_e32 v126, v126, v130
	v_mul_f32_e32 v127, v127, v132
	v_mul_f32_e32 v128, v128, v134
	v_mul_f32_e32 v129, v129, v136
	s_waitcnt lgkmcnt(3)
	v_fmac_f32_e32 v126, v162, v131
	s_waitcnt lgkmcnt(2)
	v_fmac_f32_e32 v127, v163, v133
	s_waitcnt lgkmcnt(1)
	v_fmac_f32_e32 v128, v164, v135
	s_waitcnt lgkmcnt(0)
	v_fmac_f32_e32 v129, v165, v137
	ds_bpermute_b32 v162, v167, v122
	ds_bpermute_b32 v163, v167, v123
	ds_bpermute_b32 v164, v167, v124
	ds_bpermute_b32 v165, v167, v125
	v_mul_f32_e32 v122, v122, v196
	v_mul_f32_e32 v123, v123, v198
	v_mul_f32_e32 v124, v124, v158
	v_mul_f32_e32 v125, v125, v160
	s_waitcnt lgkmcnt(3)
	v_fmac_f32_e32 v122, v162, v197
	s_waitcnt lgkmcnt(2)
	v_fmac_f32_e32 v123, v163, v199
	s_waitcnt lgkmcnt(1)
	v_fmac_f32_e32 v124, v164, v159
	s_waitcnt lgkmcnt(0)
	v_fmac_f32_e32 v125, v165, v161
	s_cmp_lg_u32 s37, 4
	s_cbranch_scc1 .Lepi_rs_0_0
	v_pk_mul_f32 v[126:127], v[126:127], s[2:3]
	v_pk_mul_f32 v[128:129], v[128:129], s[2:3]
	v_pk_mul_f32 v[122:123], v[122:123], s[2:3]
	v_pk_mul_f32 v[124:125], v[124:125], s[2:3]
